# NSA block: one static s_setprio 1 for waves 0-3 (older half) during the NSA task, reset after; on top of the GEMM static-priority version
# baseline (speedup 1.0000x reference)
; #define PIN_IDS const int tid_ = tidx_(); const int bid_ = bidx_(); (void)tid_; (void)bid_;
; DI void nsa_block(const P& p, int layer, int T, float* ldsf) {
;   PIN_IDS
;   char* ws = p.ws; char* lds = (char*)ldsf;
;   const int tid = tid_, lane = tid & 63, wid = tid >> 6, r = lane & 31, h = lane >> 5;
;   const int hd = wid & 3, half = wid >> 2, t = T * 32 + r;
;   const bf16_t* proj = (const bf16_t*)(ws + OFF_PROJ);
; DI void phase_l6(const P& p, int layer, float* ldsf) {
;     ...
;   for (int id = bid_; id < 256; id += gridDim.x) nsa_block(p, layer, 255 - id, ldsf);
.LBB0_96:
	s_sub_i32 s22, 0xff, s20
	v_mov_b32_e32 v170, v204
	s_lshl_b32 s21, s22, 5
	v_and_b32_e32 v191, 31, v170
	v_ashrrev_i32_e32 v171, 6, v170
	s_nop 0
	v_readfirstlane_b32 s0, v171
	s_cmp_lt_u32 s0, 4
	s_cbranch_scc0 .Lnsa_prio_done
	s_setprio 1
